# hand-written double-buffered RMSNorm rows in P0; fewer page items in P1 tail (WG>=130)
# baseline (speedup 1.0000x reference)
.LBB0_7:
	s_nop 0
	v_readlane_b32 s0, v254, 2
	v_readlane_b32 s1, v254, 3
	v_writelane_b32 v254, s48, 40
	s_cmp_lt_i32 s0, 1
	s_cselect_b64 s[4:5], -1, 0
	v_writelane_b32 v254, s49, 41
	v_writelane_b32 v254, s50, 42
	s_cmp_gt_i32 s1, 0
	v_writelane_b32 v254, s51, 43
	s_cselect_b64 s[6:7], -1, 0
	v_writelane_b32 v254, s52, 44
	s_and_b64 s[6:7], s[4:5], s[6:7]
	v_writelane_b32 v254, s53, 45
	s_andn2_b64 vcc, exec, s[6:7]
	v_and_b32_e32 v206, 63, v0
	v_writelane_b32 v254, s54, 46
	v_writelane_b32 v254, s55, 47
	s_cbranch_vccnz .LBB0_113
	s_movk_i32 s98, 0x2a7f
	v_readlane_b32 s0, v254, 0
	v_readlane_b32 s1, v254, 1
	s_load_dword s8, s[0:1], 0xe8
	v_readfirstlane_b32 s0, v0
	s_lshr_b32 s9, s0, 6
	s_lshl_b32 s0, s2, 3
	s_add_i32 s10, s9, s0
	s_waitcnt lgkmcnt(0)
	s_cmp_le_u32 s8, 130
	s_cbranch_scc1 .Lrc_nb
	s_sub_u32 s0, s8, 130
	s_lshl_b32 s0, s0, 3
	s_sub_u32 s98, s98, s0
.Lrc_nb:
	s_lshl_b32 s3, s8, 3
	v_readlane_b32 s14, v254, 6
	v_readlane_b32 s15, v254, 7
	v_and_b32_e32 v4, 63, v0
	v_lshlrev_b32_e32 v1, 4, v4
	v_lshlrev_b32_e32 v2, 3, v4
	v_mov_b32_e32 v3, 0x358637bd
	s_mov_b32 s20, s10
	s_mov_b32 s21, s3
	s_mov_b32 s12, 0
	s_mov_b32 s13, 0
	s_cmp_ge_u32 s20, 0x2280
	s_cbranch_scc1 .Lrms_done
	s_cmp_lt_u32 s20, 0x2000
	s_cbranch_scc1 .Lrms_i1_xp
	s_cmp_lt_u32 s20, 0x2080
	s_cbranch_scc1 .Lrms_i1_xs
	s_sub_u32 s26, s20, 0x2080
	s_lshl_b32 s0, s26, 13
	s_add_u32 s22, s80, s0
	s_addc_u32 s23, s81, 0
	s_add_u32 s24, s14, 0x4000
	s_addc_u32 s25, s15, 0
	s_lshl_b32 s0, s26, 12
	s_add_u32 s0, s0, 0x9f00000
	s_branch .Lrms_i1_c
.Lrms_i1_xs:
	s_sub_u32 s26, s20, 0x2000
	s_lshl_b32 s0, s26, 13
	s_add_u32 s22, s78, s0
	s_addc_u32 s23, s79, 0
	s_mov_b64 s[24:25], s[14:15]
	s_lshl_b32 s0, s20, 12
	s_add_u32 s0, s0, 0x7e00000
	s_branch .Lrms_i1_c
.Lrms_i1_xp:
	s_lshl_b32 s0, s20, 13
	s_add_u32 s22, s76, s0
	s_addc_u32 s23, s77, 0
	s_mov_b64 s[24:25], s[14:15]
	s_lshl_b32 s0, s20, 12
	s_add_u32 s0, s0, 0x7e00000
.Lrms_i1_c:
	s_add_u32 s28, s54, s0
	s_addc_u32 s29, s55, 0
	global_load_dwordx4 v[40:43], v1, s[22:23]
	global_load_dwordx4 v[44:47], v1, s[22:23] offset:1024
	global_load_dwordx4 v[48:51], v1, s[22:23] offset:2048
	global_load_dwordx4 v[52:55], v1, s[22:23] offset:3072
	s_add_u32 s22, s22, 0x1000
	s_addc_u32 s23, s23, 0
	global_load_dwordx4 v[56:59], v1, s[22:23]
	global_load_dwordx4 v[60:63], v1, s[22:23] offset:1024
	global_load_dwordx4 v[64:67], v1, s[22:23] offset:2048
	global_load_dwordx4 v[68:71], v1, s[22:23] offset:3072
	global_load_dwordx4 v[72:75], v1, s[24:25]
	global_load_dwordx4 v[76:79], v1, s[24:25] offset:1024
	global_load_dwordx4 v[80:83], v1, s[24:25] offset:2048
	global_load_dwordx4 v[84:87], v1, s[24:25] offset:3072
	s_add_u32 s24, s24, 0x1000
	s_addc_u32 s25, s25, 0
	global_load_dwordx4 v[88:91], v1, s[24:25]
	global_load_dwordx4 v[92:95], v1, s[24:25] offset:1024
	global_load_dwordx4 v[96:99], v1, s[24:25] offset:2048
	global_load_dwordx4 v[100:103], v1, s[24:25] offset:3072
	s_add_u32 s20, s20, s21
	s_mov_b32 s12, 1
	s_cmp_ge_u32 s20, 0x2280
	s_cbranch_scc1 .Lrms_first
	s_cmp_lt_u32 s20, 0x2000
	s_cbranch_scc1 .Lrms_i2_xp
	s_cmp_lt_u32 s20, 0x2080
	s_cbranch_scc1 .Lrms_i2_xs
	s_sub_u32 s26, s20, 0x2080
	s_lshl_b32 s0, s26, 13
	s_add_u32 s22, s80, s0
	s_addc_u32 s23, s81, 0
	s_add_u32 s24, s14, 0x4000
	s_addc_u32 s25, s15, 0
	s_lshl_b32 s0, s26, 12
	s_add_u32 s0, s0, 0x9f00000
	s_branch .Lrms_i2_c

.Lrms_i2_c:
	s_add_u32 s30, s54, s0
	s_addc_u32 s31, s55, 0
	global_load_dwordx4 v[104:107], v1, s[22:23]
	global_load_dwordx4 v[108:111], v1, s[22:23] offset:1024
	global_load_dwordx4 v[112:115], v1, s[22:23] offset:2048
	global_load_dwordx4 v[116:119], v1, s[22:23] offset:3072
	s_add_u32 s22, s22, 0x1000
	s_addc_u32 s23, s23, 0
	global_load_dwordx4 v[120:123], v1, s[22:23]
	global_load_dwordx4 v[124:127], v1, s[22:23] offset:1024
	global_load_dwordx4 v[128:131], v1, s[22:23] offset:2048
	global_load_dwordx4 v[132:135], v1, s[22:23] offset:3072
	global_load_dwordx4 v[136:139], v1, s[24:25]
	global_load_dwordx4 v[140:143], v1, s[24:25] offset:1024
	global_load_dwordx4 v[144:147], v1, s[24:25] offset:2048
	global_load_dwordx4 v[148:151], v1, s[24:25] offset:3072
	s_add_u32 s24, s24, 0x1000
	s_addc_u32 s25, s25, 0
	global_load_dwordx4 v[152:155], v1, s[24:25]
	global_load_dwordx4 v[156:159], v1, s[24:25] offset:1024
	global_load_dwordx4 v[160:163], v1, s[24:25] offset:2048
	global_load_dwordx4 v[164:167], v1, s[24:25] offset:3072
	s_add_u32 s20, s20, s21
	s_mov_b32 s13, 1
.Lrms_first:
	s_cmp_eq_u32 s13, 0
	s_cbranch_scc1 .Lrms_f0
	s_waitcnt vmcnt(16)
	s_branch .Lrms_sA_go

.Lrms_sA:
	s_cmp_eq_u32 s13, 0
	s_cbranch_scc1 .Lrms_sA_w0
	s_waitcnt vmcnt(24)
	s_branch .Lrms_sA_go

.Lrms_sA_go:
	v_mul_f32_e32 v4, v41, v41
	v_mul_f32_e32 v5, v43, v43
	v_fmac_f32_e32 v4, v40, v40
	v_fmac_f32_e32 v5, v42, v42
	v_add_f32_e32 v6, v4, v5
	v_mul_f32_e32 v4, v45, v45
	v_mul_f32_e32 v5, v47, v47
	v_fmac_f32_e32 v4, v44, v44
	v_fmac_f32_e32 v5, v46, v46
	v_add_f32_e32 v4, v4, v5
	v_add_f32_e32 v6, v6, v4
	v_mul_f32_e32 v4, v49, v49
	v_mul_f32_e32 v5, v51, v51
	v_fmac_f32_e32 v4, v48, v48
	v_fmac_f32_e32 v5, v50, v50
	v_add_f32_e32 v4, v4, v5
	v_add_f32_e32 v6, v6, v4
	v_mul_f32_e32 v4, v53, v53
	v_mul_f32_e32 v5, v55, v55
	v_fmac_f32_e32 v4, v52, v52
	v_fmac_f32_e32 v5, v54, v54
	v_add_f32_e32 v4, v4, v5
	v_add_f32_e32 v6, v6, v4
	v_mul_f32_e32 v4, v57, v57
	v_mul_f32_e32 v5, v59, v59
	v_fmac_f32_e32 v4, v56, v56
	v_fmac_f32_e32 v5, v58, v58
	v_add_f32_e32 v4, v4, v5
	v_add_f32_e32 v6, v6, v4
	v_mul_f32_e32 v4, v61, v61
	v_mul_f32_e32 v5, v63, v63
	v_fmac_f32_e32 v4, v60, v60
	v_fmac_f32_e32 v5, v62, v62
	v_add_f32_e32 v4, v4, v5
	v_add_f32_e32 v6, v6, v4
	v_mul_f32_e32 v4, v65, v65
	v_mul_f32_e32 v5, v67, v67
	v_fmac_f32_e32 v4, v64, v64
	v_fmac_f32_e32 v5, v66, v66
	v_add_f32_e32 v4, v4, v5
	v_add_f32_e32 v6, v6, v4
	v_mul_f32_e32 v4, v69, v69
	v_mul_f32_e32 v5, v71, v71
	v_fmac_f32_e32 v4, v68, v68
	v_fmac_f32_e32 v5, v70, v70
	v_add_f32_e32 v4, v4, v5
	v_add_f32_e32 v6, v6, v4
	s_nop 1
	v_add_f32_dpp v6, v6, v6 quad_perm:[1,0,3,2] row_mask:0xf bank_mask:0xf bound_ctrl:1
	s_nop 1
	v_add_f32_dpp v6, v6, v6 quad_perm:[2,3,0,1] row_mask:0xf bank_mask:0xf bound_ctrl:1
	s_nop 1
	v_add_f32_dpp v6, v6, v6 row_half_mirror row_mask:0xf bank_mask:0xf bound_ctrl:1
	s_nop 1
	v_add_f32_dpp v6, v6, v6 row_mirror row_mask:0xf bank_mask:0xf bound_ctrl:1
	v_mov_b32_e32 v7, v6
	s_nop 1
	v_permlane16_swap_b32_e32 v6, v7
	v_add_f32_e32 v6, v6, v7
	v_mov_b32_e32 v7, v6
	s_nop 1
	v_permlane32_swap_b32_e32 v6, v7
	v_add_f32_e32 v6, v6, v7
	v_fmamk_f32 v6, v6, 0x3a000000, v3
	v_rsq_f32_e32 v7, v6
	s_nop 0
	v_mul_f32_e32 v40, v40, v7
	v_mul_f32_e32 v40, v72, v40
	v_mul_f32_e32 v41, v41, v7
	v_mul_f32_e32 v41, v73, v41
	v_mul_f32_e32 v42, v42, v7
	v_mul_f32_e32 v42, v74, v42
	v_mul_f32_e32 v43, v43, v7
	v_mul_f32_e32 v43, v75, v43
	v_cvt_pk_bf16_f32 v40, v40, v41
	v_cvt_pk_bf16_f32 v41, v42, v43
	global_store_dwordx2 v2, v[40:41], s[28:29]
	v_mul_f32_e32 v44, v44, v7
	v_mul_f32_e32 v44, v76, v44
	v_mul_f32_e32 v45, v45, v7
	v_mul_f32_e32 v45, v77, v45
	v_mul_f32_e32 v46, v46, v7
	v_mul_f32_e32 v46, v78, v46
	v_mul_f32_e32 v47, v47, v7
	v_mul_f32_e32 v47, v79, v47
	v_cvt_pk_bf16_f32 v44, v44, v45
	v_cvt_pk_bf16_f32 v45, v46, v47
	global_store_dwordx2 v2, v[44:45], s[28:29] offset:512
	v_mul_f32_e32 v48, v48, v7
	v_mul_f32_e32 v48, v80, v48
	v_mul_f32_e32 v49, v49, v7
	v_mul_f32_e32 v49, v81, v49
	v_mul_f32_e32 v50, v50, v7
	v_mul_f32_e32 v50, v82, v50
	v_mul_f32_e32 v51, v51, v7
	v_mul_f32_e32 v51, v83, v51
	v_cvt_pk_bf16_f32 v48, v48, v49
	v_cvt_pk_bf16_f32 v49, v50, v51
	global_store_dwordx2 v2, v[48:49], s[28:29] offset:1024
	v_mul_f32_e32 v52, v52, v7
	v_mul_f32_e32 v52, v84, v52
	v_mul_f32_e32 v53, v53, v7
	v_mul_f32_e32 v53, v85, v53
	v_mul_f32_e32 v54, v54, v7
	v_mul_f32_e32 v54, v86, v54
	v_mul_f32_e32 v55, v55, v7
	v_mul_f32_e32 v55, v87, v55
	v_cvt_pk_bf16_f32 v52, v52, v53
	v_cvt_pk_bf16_f32 v53, v54, v55
	global_store_dwordx2 v2, v[52:53], s[28:29] offset:1536
	v_mul_f32_e32 v56, v56, v7
	v_mul_f32_e32 v56, v88, v56
	v_mul_f32_e32 v57, v57, v7
	v_mul_f32_e32 v57, v89, v57
	v_mul_f32_e32 v58, v58, v7
	v_mul_f32_e32 v58, v90, v58
	v_mul_f32_e32 v59, v59, v7
	v_mul_f32_e32 v59, v91, v59
	v_cvt_pk_bf16_f32 v56, v56, v57
	v_cvt_pk_bf16_f32 v57, v58, v59
	global_store_dwordx2 v2, v[56:57], s[28:29] offset:2048
	v_mul_f32_e32 v60, v60, v7
	v_mul_f32_e32 v60, v92, v60
	v_mul_f32_e32 v61, v61, v7
	v_mul_f32_e32 v61, v93, v61
	v_mul_f32_e32 v62, v62, v7
	v_mul_f32_e32 v62, v94, v62
	v_mul_f32_e32 v63, v63, v7
	v_mul_f32_e32 v63, v95, v63
	v_cvt_pk_bf16_f32 v60, v60, v61
	v_cvt_pk_bf16_f32 v61, v62, v63
	global_store_dwordx2 v2, v[60:61], s[28:29] offset:2560
	v_mul_f32_e32 v64, v64, v7
	v_mul_f32_e32 v64, v96, v64
	v_mul_f32_e32 v65, v65, v7
	v_mul_f32_e32 v65, v97, v65
	v_mul_f32_e32 v66, v66, v7
	v_mul_f32_e32 v66, v98, v66
	v_mul_f32_e32 v67, v67, v7
	v_mul_f32_e32 v67, v99, v67
	v_cvt_pk_bf16_f32 v64, v64, v65
	v_cvt_pk_bf16_f32 v65, v66, v67
	global_store_dwordx2 v2, v[64:65], s[28:29] offset:3072
	v_mul_f32_e32 v68, v68, v7
	v_mul_f32_e32 v68, v100, v68
	v_mul_f32_e32 v69, v69, v7
	v_mul_f32_e32 v69, v101, v69
	v_mul_f32_e32 v70, v70, v7
	v_mul_f32_e32 v70, v102, v70
	v_mul_f32_e32 v71, v71, v7
	v_mul_f32_e32 v71, v103, v71
	v_cvt_pk_bf16_f32 v68, v68, v69
	v_cvt_pk_bf16_f32 v69, v70, v71
	global_store_dwordx2 v2, v[68:69], s[28:29] offset:3584
	s_mov_b32 s12, 0
	s_cmp_ge_u32 s20, 0x2280
	s_cbranch_scc1 .Lrms_sA_ni
	s_cmp_lt_u32 s20, 0x2000
	s_cbranch_scc1 .Lrms_i3_xp
	s_cmp_lt_u32 s20, 0x2080
	s_cbranch_scc1 .Lrms_i3_xs
	s_sub_u32 s26, s20, 0x2080
	s_lshl_b32 s0, s26, 13
	s_add_u32 s22, s80, s0
	s_addc_u32 s23, s81, 0
	s_add_u32 s24, s14, 0x4000
	s_addc_u32 s25, s15, 0
	s_lshl_b32 s0, s26, 12
	s_add_u32 s0, s0, 0x9f00000
	s_branch .Lrms_i3_c

.Lrms_i3_c:
	s_add_u32 s28, s54, s0
	s_addc_u32 s29, s55, 0
	global_load_dwordx4 v[40:43], v1, s[22:23]
	global_load_dwordx4 v[44:47], v1, s[22:23] offset:1024
	global_load_dwordx4 v[48:51], v1, s[22:23] offset:2048
	global_load_dwordx4 v[52:55], v1, s[22:23] offset:3072
	s_add_u32 s22, s22, 0x1000
	s_addc_u32 s23, s23, 0
	global_load_dwordx4 v[56:59], v1, s[22:23]
	global_load_dwordx4 v[60:63], v1, s[22:23] offset:1024
	global_load_dwordx4 v[64:67], v1, s[22:23] offset:2048
	global_load_dwordx4 v[68:71], v1, s[22:23] offset:3072
	global_load_dwordx4 v[72:75], v1, s[24:25]
	global_load_dwordx4 v[76:79], v1, s[24:25] offset:1024
	global_load_dwordx4 v[80:83], v1, s[24:25] offset:2048
	global_load_dwordx4 v[84:87], v1, s[24:25] offset:3072
	s_add_u32 s24, s24, 0x1000
	s_addc_u32 s25, s25, 0
	global_load_dwordx4 v[88:91], v1, s[24:25]
	global_load_dwordx4 v[92:95], v1, s[24:25] offset:1024
	global_load_dwordx4 v[96:99], v1, s[24:25] offset:2048
	global_load_dwordx4 v[100:103], v1, s[24:25] offset:3072
	s_add_u32 s20, s20, s21
	s_mov_b32 s12, 1
.Lrms_sA_ni:
	s_cmp_eq_u32 s13, 0
	s_cbranch_scc1 .Lrms_done
.Lrms_sB:
	s_cmp_eq_u32 s12, 0
	s_cbranch_scc1 .Lrms_sB_w0
	s_waitcnt vmcnt(24)
	s_branch .Lrms_sB_go

.Lrms_sB_go:
	v_mul_f32_e32 v4, v105, v105
	v_mul_f32_e32 v5, v107, v107
	v_fmac_f32_e32 v4, v104, v104
	v_fmac_f32_e32 v5, v106, v106
	v_add_f32_e32 v6, v4, v5
	v_mul_f32_e32 v4, v109, v109
	v_mul_f32_e32 v5, v111, v111
	v_fmac_f32_e32 v4, v108, v108
	v_fmac_f32_e32 v5, v110, v110
	v_add_f32_e32 v4, v4, v5
	v_add_f32_e32 v6, v6, v4
	v_mul_f32_e32 v4, v113, v113
	v_mul_f32_e32 v5, v115, v115
	v_fmac_f32_e32 v4, v112, v112
	v_fmac_f32_e32 v5, v114, v114
	v_add_f32_e32 v4, v4, v5
	v_add_f32_e32 v6, v6, v4
	v_mul_f32_e32 v4, v117, v117
	v_mul_f32_e32 v5, v119, v119
	v_fmac_f32_e32 v4, v116, v116
	v_fmac_f32_e32 v5, v118, v118
	v_add_f32_e32 v4, v4, v5
	v_add_f32_e32 v6, v6, v4
	v_mul_f32_e32 v4, v121, v121
	v_mul_f32_e32 v5, v123, v123
	v_fmac_f32_e32 v4, v120, v120
	v_fmac_f32_e32 v5, v122, v122
	v_add_f32_e32 v4, v4, v5
	v_add_f32_e32 v6, v6, v4
	v_mul_f32_e32 v4, v125, v125
	v_mul_f32_e32 v5, v127, v127
	v_fmac_f32_e32 v4, v124, v124
	v_fmac_f32_e32 v5, v126, v126
	v_add_f32_e32 v4, v4, v5
	v_add_f32_e32 v6, v6, v4
	v_mul_f32_e32 v4, v129, v129
	v_mul_f32_e32 v5, v131, v131
	v_fmac_f32_e32 v4, v128, v128
	v_fmac_f32_e32 v5, v130, v130
	v_add_f32_e32 v4, v4, v5
	v_add_f32_e32 v6, v6, v4
	v_mul_f32_e32 v4, v133, v133
	v_mul_f32_e32 v5, v135, v135
	v_fmac_f32_e32 v4, v132, v132
	v_fmac_f32_e32 v5, v134, v134
	v_add_f32_e32 v4, v4, v5
	v_add_f32_e32 v6, v6, v4
	s_nop 1
	v_add_f32_dpp v6, v6, v6 quad_perm:[1,0,3,2] row_mask:0xf bank_mask:0xf bound_ctrl:1
	s_nop 1
	v_add_f32_dpp v6, v6, v6 quad_perm:[2,3,0,1] row_mask:0xf bank_mask:0xf bound_ctrl:1
	s_nop 1
	v_add_f32_dpp v6, v6, v6 row_half_mirror row_mask:0xf bank_mask:0xf bound_ctrl:1
	s_nop 1
	v_add_f32_dpp v6, v6, v6 row_mirror row_mask:0xf bank_mask:0xf bound_ctrl:1
	v_mov_b32_e32 v7, v6
	s_nop 1
	v_permlane16_swap_b32_e32 v6, v7
	v_add_f32_e32 v6, v6, v7
	v_mov_b32_e32 v7, v6
	s_nop 1
	v_permlane32_swap_b32_e32 v6, v7
	v_add_f32_e32 v6, v6, v7
	v_fmamk_f32 v6, v6, 0x3a000000, v3
	v_rsq_f32_e32 v7, v6
	s_nop 0
	v_mul_f32_e32 v104, v104, v7
	v_mul_f32_e32 v104, v136, v104
	v_mul_f32_e32 v105, v105, v7
	v_mul_f32_e32 v105, v137, v105
	v_mul_f32_e32 v106, v106, v7
	v_mul_f32_e32 v106, v138, v106
	v_mul_f32_e32 v107, v107, v7
	v_mul_f32_e32 v107, v139, v107
	v_cvt_pk_bf16_f32 v104, v104, v105
	v_cvt_pk_bf16_f32 v105, v106, v107
	global_store_dwordx2 v2, v[104:105], s[30:31]
	v_mul_f32_e32 v108, v108, v7
	v_mul_f32_e32 v108, v140, v108
	v_mul_f32_e32 v109, v109, v7
	v_mul_f32_e32 v109, v141, v109
	v_mul_f32_e32 v110, v110, v7
	v_mul_f32_e32 v110, v142, v110
	v_mul_f32_e32 v111, v111, v7
	v_mul_f32_e32 v111, v143, v111
	v_cvt_pk_bf16_f32 v108, v108, v109
	v_cvt_pk_bf16_f32 v109, v110, v111
	global_store_dwordx2 v2, v[108:109], s[30:31] offset:512
	v_mul_f32_e32 v112, v112, v7
	v_mul_f32_e32 v112, v144, v112
	v_mul_f32_e32 v113, v113, v7
	v_mul_f32_e32 v113, v145, v113
	v_mul_f32_e32 v114, v114, v7
	v_mul_f32_e32 v114, v146, v114
	v_mul_f32_e32 v115, v115, v7
	v_mul_f32_e32 v115, v147, v115
	v_cvt_pk_bf16_f32 v112, v112, v113
	v_cvt_pk_bf16_f32 v113, v114, v115
	global_store_dwordx2 v2, v[112:113], s[30:31] offset:1024
	v_mul_f32_e32 v116, v116, v7
	v_mul_f32_e32 v116, v148, v116
	v_mul_f32_e32 v117, v117, v7
	v_mul_f32_e32 v117, v149, v117
	v_mul_f32_e32 v118, v118, v7
	v_mul_f32_e32 v118, v150, v118
	v_mul_f32_e32 v119, v119, v7
	v_mul_f32_e32 v119, v151, v119
	v_cvt_pk_bf16_f32 v116, v116, v117
	v_cvt_pk_bf16_f32 v117, v118, v119
	global_store_dwordx2 v2, v[116:117], s[30:31] offset:1536
	v_mul_f32_e32 v120, v120, v7
	v_mul_f32_e32 v120, v152, v120
	v_mul_f32_e32 v121, v121, v7
	v_mul_f32_e32 v121, v153, v121
	v_mul_f32_e32 v122, v122, v7
	v_mul_f32_e32 v122, v154, v122
	v_mul_f32_e32 v123, v123, v7
	v_mul_f32_e32 v123, v155, v123
	v_cvt_pk_bf16_f32 v120, v120, v121
	v_cvt_pk_bf16_f32 v121, v122, v123
	global_store_dwordx2 v2, v[120:121], s[30:31] offset:2048
	v_mul_f32_e32 v124, v124, v7
	v_mul_f32_e32 v124, v156, v124
	v_mul_f32_e32 v125, v125, v7
	v_mul_f32_e32 v125, v157, v125
	v_mul_f32_e32 v126, v126, v7
	v_mul_f32_e32 v126, v158, v126
	v_mul_f32_e32 v127, v127, v7
	v_mul_f32_e32 v127, v159, v127
	v_cvt_pk_bf16_f32 v124, v124, v125
	v_cvt_pk_bf16_f32 v125, v126, v127
	global_store_dwordx2 v2, v[124:125], s[30:31] offset:2560
	v_mul_f32_e32 v128, v128, v7
	v_mul_f32_e32 v128, v160, v128
	v_mul_f32_e32 v129, v129, v7
	v_mul_f32_e32 v129, v161, v129
	v_mul_f32_e32 v130, v130, v7
	v_mul_f32_e32 v130, v162, v130
	v_mul_f32_e32 v131, v131, v7
	v_mul_f32_e32 v131, v163, v131
	v_cvt_pk_bf16_f32 v128, v128, v129
	v_cvt_pk_bf16_f32 v129, v130, v131
	global_store_dwordx2 v2, v[128:129], s[30:31] offset:3072
	v_mul_f32_e32 v132, v132, v7
	v_mul_f32_e32 v132, v164, v132
	v_mul_f32_e32 v133, v133, v7
	v_mul_f32_e32 v133, v165, v133
	v_mul_f32_e32 v134, v134, v7
	v_mul_f32_e32 v134, v166, v134
	v_mul_f32_e32 v135, v135, v7
	v_mul_f32_e32 v135, v167, v135
	v_cvt_pk_bf16_f32 v132, v132, v133
	v_cvt_pk_bf16_f32 v133, v134, v135
	global_store_dwordx2 v2, v[132:133], s[30:31] offset:3584
	s_mov_b32 s13, 0
	s_cmp_ge_u32 s20, 0x2280
	s_cbranch_scc1 .Lrms_sB_ni
	s_cmp_lt_u32 s20, 0x2000
	s_cbranch_scc1 .Lrms_i4_xp
	s_cmp_lt_u32 s20, 0x2080
	s_cbranch_scc1 .Lrms_i4_xs
	s_sub_u32 s26, s20, 0x2080
	s_lshl_b32 s0, s26, 13
	s_add_u32 s22, s80, s0
	s_addc_u32 s23, s81, 0
	s_add_u32 s24, s14, 0x4000
	s_addc_u32 s25, s15, 0
	s_lshl_b32 s0, s26, 12
	s_add_u32 s0, s0, 0x9f00000
	s_branch .Lrms_i4_c

.Lrms_sB_ni:
	s_cmp_eq_u32 s12, 0
	s_cbranch_scc1 .Lrms_done
	s_branch .Lrms_sA
.Lrms_done:
	s_cmpk_gt_i32 s10, 0x267f
	v_and_b32_e32 v34, 63, v0
	s_cbranch_scc1 .LBB0_78
	s_mov_b64 exec, -1
	v_readlane_b32 s0, v254, 0
	v_readlane_b32 s1, v254, 1
	s_nop 4
	s_load_dwordx2 s[56:57], s[0:1], 0x50
	s_load_dwordx2 s[58:59], s[0:1], 0x98
	s_load_dwordx2 s[60:61], s[0:1], 0x60
	s_load_dwordx2 s[62:63], s[0:1], 0xd8
	s_load_dwordx2 s[64:65], s[0:1], 0x48
	v_readfirstlane_b32 s4, v0
	v_and_b32_e32 v7, 63, v0
	s_lshr_b32 s4, s4, 6
	v_lshrrev_b32_e32 v1, 3, v7
	v_and_b32_e32 v2, 7, v7
	s_lshl_b32 s5, s4, 14
	v_lshlrev_b32_e32 v5, 5, v2
	s_movk_i32 s18, 0x420
	v_mul_u32_u24_e32 v4, s18, v2
	v_lshlrev_b32_e32 v2, 4, v2
	s_movk_i32 s18, 0x84
	v_mad_u32_u24 v3, v1, s18, v2
	v_lshl_add_u32 v4, v1, 2, v4
	v_add_u32_e32 v3, s5, v3
	v_add_u32_e32 v4, s5, v4
	v_mov_b32_e32 v148, v3
	v_add_u32_e32 v149, 1056, v3
	v_add_u32_e32 v150, 2112, v3
	v_add_u32_e32 v151, 3168, v3
	v_add_u32_e32 v152, 4224, v3
	v_add_u32_e32 v153, 5280, v3
	v_add_u32_e32 v154, 6336, v3
	v_add_u32_e32 v155, 7392, v3
	s_waitcnt lgkmcnt(0)
	s_mov_b32 s20, s10
	s_mov_b32 s21, s3
	s_cmp_ge_u32 s20, 0x2680
	s_cbranch_scc1 .LBB0_78
	s_mov_b32 s26, s20
	s_cmp_lt_u32 s26, 0x2080
	s_cbranch_scc1 .Ltrp0_i1_s0
	s_sub_u32 s26, s26, 0x2080
	s_cmp_lt_u32 s26, 0x400
	s_cbranch_scc1 .Ltrp0_i1_s1
	s_sub_u32 s26, s26, 0x400
	s_cmp_lt_u32 s26, 0x100
	s_cbranch_scc1 .Ltrp0_i1_s2
	s_sub_u32 s26, s26, 0x100
	s_branch .Ltrp0_i1_s3

.LBB0_80:
	s_branch .LBB0_81
	global_load_dwordx4 v[2:5], v26, s[4:5]
	global_load_dwordx4 v[6:9], v26, s[4:5] offset:1024
	global_load_dwordx4 v[10:13], v26, s[4:5] offset:2048
	global_load_dwordx4 v[14:17], v26, s[4:5] offset:3072
	v_lshl_add_u64 v[18:19], s[4:5], 0, v[26:27]
	v_add_co_u32_e32 v78, vcc, s30, v18
	s_lshl_b64 s[4:5], s[10:11], 12
	s_nop 0
	v_addc_co_u32_e32 v79, vcc, 0, v19, vcc
	global_load_dwordx4 v[18:21], v[78:79], off
	global_load_dwordx4 v[22:25], v[78:79], off offset:1024
	global_load_dwordx4 v[74:77], v[78:79], off offset:2048
	s_nop 0
	global_load_dwordx4 v[78:81], v[78:79], off offset:3072
	s_nop 0
	global_load_dwordx4 v[82:85], v[36:37], off
	s_waitcnt vmcnt(8)
	v_mul_f32_e32 v86, v3, v3
	v_mul_f32_e32 v87, v5, v5
	s_waitcnt vmcnt(7)
	v_mul_f32_e32 v88, v7, v7
	v_mul_f32_e32 v89, v9, v9
	s_waitcnt vmcnt(6)
	v_mul_f32_e32 v90, v11, v11
	v_mul_f32_e32 v91, v13, v13
	v_fmac_f32_e32 v86, v2, v2
	v_fmac_f32_e32 v87, v4, v4
	v_fmac_f32_e32 v88, v6, v6
	v_fmac_f32_e32 v89, v8, v8
	s_waitcnt vmcnt(5)
	v_mul_f32_e32 v92, v15, v15
	v_mul_f32_e32 v93, v17, v17
	v_fmac_f32_e32 v90, v10, v10
	v_fmac_f32_e32 v91, v12, v12
	v_add_f32_e32 v86, v86, v87
	v_add_f32_e32 v87, v88, v89
	v_fmac_f32_e32 v92, v14, v14
	v_fmac_f32_e32 v93, v16, v16
	v_add_f32_e32 v88, v90, v91
	s_waitcnt vmcnt(4)
	v_mul_f32_e32 v90, v19, v19
	v_mul_f32_e32 v91, v21, v21
	v_add_f32_e32 v86, v86, v87
	v_add_f32_e32 v89, v92, v93
	s_waitcnt vmcnt(3)
	v_mul_f32_e32 v92, v23, v23
	v_mul_f32_e32 v93, v25, v25
	v_fmac_f32_e32 v90, v18, v18
	v_fmac_f32_e32 v91, v20, v20
	v_add_f32_e32 v86, v86, v88
	s_waitcnt vmcnt(2)
	v_mul_f32_e32 v94, v75, v75
	v_mul_f32_e32 v95, v77, v77
	v_fmac_f32_e32 v92, v22, v22
	v_fmac_f32_e32 v93, v24, v24
	v_add_f32_e32 v87, v90, v91
	v_add_f32_e32 v86, v86, v89
	s_waitcnt vmcnt(1)
	v_mul_f32_e32 v96, v79, v79
	v_mul_f32_e32 v97, v81, v81
	v_fmac_f32_e32 v94, v74, v74
	v_fmac_f32_e32 v95, v76, v76
	v_add_f32_e32 v88, v92, v93
	v_add_f32_e32 v86, v86, v87
	v_fmac_f32_e32 v96, v78, v78
	v_fmac_f32_e32 v97, v80, v80
	v_add_f32_e32 v90, v94, v95
	v_add_f32_e32 v86, v86, v88
	v_add_f32_e32 v91, v96, v97
	v_add_f32_e32 v86, v86, v90
	v_add_f32_e32 v86, v86, v91
	s_nop 1
	v_add_f32_dpp v86, v86, v86 quad_perm:[1,0,3,2] row_mask:0xf bank_mask:0xf bound_ctrl:1
	s_nop 1
	v_add_f32_dpp v86, v86, v86 quad_perm:[2,3,0,1] row_mask:0xf bank_mask:0xf bound_ctrl:1
	s_nop 1
	v_add_f32_dpp v86, v86, v86 row_half_mirror row_mask:0xf bank_mask:0xf bound_ctrl:1
	s_nop 1
	v_add_f32_dpp v86, v86, v86 row_mirror row_mask:0xf bank_mask:0xf bound_ctrl:1
	v_mov_b32_e32 v87, v86
	s_nop 1
	v_permlane16_swap_b32_e32 v86, v87
	v_add_f32_e32 v86, v86, v87
	v_mov_b32_e32 v87, v86
	s_nop 1
	v_permlane32_swap_b32_e32 v86, v87
	v_add_f32_e32 v86, v86, v87
	v_fmamk_f32 v86, v86, 0x3a000000, v35
	v_mul_f32_e32 v87, 0x4b800000, v86
	v_cmp_gt_f32_e32 vcc, s45, v86
	s_nop 1
	v_cndmask_b32_e32 v86, v86, v87, vcc
	v_rsq_f32_e32 v88, v86
	v_lshl_add_u64 v[86:87], v[50:51], 0, s[4:5]
	v_mul_f32_e32 v89, 0x45800000, v88
	v_cndmask_b32_e32 v88, v88, v89, vcc
	v_pk_mul_f32 v[2:3], v[2:3], v[88:89] op_sel_hi:[1,0]
	v_pk_mul_f32 v[4:5], v[4:5], v[88:89] op_sel_hi:[1,0]
	s_waitcnt vmcnt(0)
	v_pk_mul_f32 v[2:3], v[82:83], v[2:3]
	v_pk_mul_f32 v[4:5], v[84:85], v[4:5]
	v_cvt_pk_bf16_f32 v2, v2, v3
	v_pk_mul_f32 v[6:7], v[6:7], v[88:89] op_sel_hi:[1,0]
	v_cvt_pk_bf16_f32 v3, v4, v5
	global_store_dwordx2 v[86:87], v[2:3], off
	global_load_dwordx4 v[2:5], v[36:37], off offset:1024
	v_pk_mul_f32 v[8:9], v[8:9], v[88:89] op_sel_hi:[1,0]
	s_waitcnt vmcnt(0)
	v_pk_mul_f32 v[2:3], v[2:3], v[6:7]
	v_pk_mul_f32 v[4:5], v[4:5], v[8:9]
	v_cvt_pk_bf16_f32 v2, v2, v3
	v_pk_mul_f32 v[6:7], v[10:11], v[88:89] op_sel_hi:[1,0]
	v_cvt_pk_bf16_f32 v3, v4, v5
	global_store_dwordx2 v[86:87], v[2:3], off offset:512
	global_load_dwordx4 v[2:5], v[36:37], off offset:2048
	v_pk_mul_f32 v[8:9], v[12:13], v[88:89] op_sel_hi:[1,0]
	s_waitcnt vmcnt(0)
	v_pk_mul_f32 v[2:3], v[2:3], v[6:7]
	v_pk_mul_f32 v[4:5], v[4:5], v[8:9]
	v_cvt_pk_bf16_f32 v2, v2, v3
	v_pk_mul_f32 v[6:7], v[14:15], v[88:89] op_sel_hi:[1,0]
	v_cvt_pk_bf16_f32 v3, v4, v5
	global_store_dwordx2 v[86:87], v[2:3], off offset:1024
	global_load_dwordx4 v[2:5], v[36:37], off offset:3072
	v_pk_mul_f32 v[8:9], v[16:17], v[88:89] op_sel_hi:[1,0]
	s_waitcnt vmcnt(0)
	v_pk_mul_f32 v[2:3], v[6:7], v[2:3]
	v_pk_mul_f32 v[4:5], v[8:9], v[4:5]
	v_cvt_pk_bf16_f32 v2, v2, v3
	v_pk_mul_f32 v[6:7], v[18:19], v[88:89] op_sel_hi:[1,0]
	v_cvt_pk_bf16_f32 v3, v4, v5
	global_store_dwordx2 v[86:87], v[2:3], off offset:1536
	global_load_dwordx4 v[2:5], v[52:53], off
	v_pk_mul_f32 v[8:9], v[20:21], v[88:89] op_sel_hi:[1,0]
	s_waitcnt vmcnt(0)
	v_pk_mul_f32 v[2:3], v[6:7], v[2:3]
	v_pk_mul_f32 v[4:5], v[8:9], v[4:5]
	v_cvt_pk_bf16_f32 v2, v2, v3
	v_pk_mul_f32 v[6:7], v[22:23], v[88:89] op_sel_hi:[1,0]
	v_cvt_pk_bf16_f32 v3, v4, v5
	global_store_dwordx2 v[86:87], v[2:3], off offset:2048
	global_load_dwordx4 v[2:5], v[54:55], off
	v_pk_mul_f32 v[8:9], v[24:25], v[88:89] op_sel_hi:[1,0]
	s_waitcnt vmcnt(0)
	v_pk_mul_f32 v[2:3], v[6:7], v[2:3]
	v_pk_mul_f32 v[4:5], v[8:9], v[4:5]
	v_cvt_pk_bf16_f32 v2, v2, v3
	v_pk_mul_f32 v[6:7], v[74:75], v[88:89] op_sel_hi:[1,0]
	v_cvt_pk_bf16_f32 v3, v4, v5
	global_store_dwordx2 v[86:87], v[2:3], off offset:2560
	global_load_dwordx4 v[2:5], v[56:57], off
	v_pk_mul_f32 v[8:9], v[76:77], v[88:89] op_sel_hi:[1,0]
	s_waitcnt vmcnt(0)
	v_pk_mul_f32 v[2:3], v[6:7], v[2:3]
	v_pk_mul_f32 v[4:5], v[8:9], v[4:5]
	v_cvt_pk_bf16_f32 v2, v2, v3
	v_pk_mul_f32 v[6:7], v[78:79], v[88:89] op_sel_hi:[1,0]
	v_cvt_pk_bf16_f32 v3, v4, v5
	global_store_dwordx2 v[86:87], v[2:3], off offset:3072
	global_load_dwordx4 v[2:5], v[58:59], off
	v_pk_mul_f32 v[8:9], v[80:81], v[88:89] op_sel_hi:[1,0]
	s_waitcnt vmcnt(0)
	v_pk_mul_f32 v[2:3], v[6:7], v[2:3]
	v_pk_mul_f32 v[4:5], v[8:9], v[4:5]
	v_cvt_pk_bf16_f32 v2, v2, v3
	s_nop 0
	v_cvt_pk_bf16_f32 v3, v4, v5
	global_store_dwordx2 v[86:87], v[2:3], off offset:3584

.LBB0_325:
	s_cmp_eq_u32 s99, 5
	s_cbranch_scc0 .Lrc_p1skip
	s_cmp_lt_u32 s100, 130
	s_cbranch_scc1 .Lrc_p1skip
	s_mov_b32 s99, 7
	s_mov_b64 exec, -1
	v_readlane_b32 s0, v254, 0
	v_readlane_b32 s1, v254, 1
	v_readlane_b32 s52, v254, 44
	v_readlane_b32 s53, v254, 45
	v_readlane_b32 s54, v254, 46
	v_readlane_b32 s55, v254, 47
	s_nop 4
	s_load_dwordx16 s[76:91], s[0:1], 0x0
	s_load_dword s8, s[0:1], 0xe8
	s_waitcnt lgkmcnt(0)
	s_add_u32 s2, s100, 0x550
	s_sub_u32 s2, s2, s8
	s_sub_u32 s8, s8, 130
	s_movk_i32 s98, 0x2a7f
	v_readfirstlane_b32 s9, v0
	s_lshr_b32 s9, s9, 6
	s_lshl_b32 s10, s2, 3
	s_add_u32 s10, s10, s9
	s_lshl_b32 s3, s8, 3
	v_and_b32_e32 v34, 63, v0
	s_branch .LBB0_78
